# adds: leaders poll the cross-XCD arrival counter instead of the release word; census loads in flight
# speedup vs baseline: 1.0192x; 1.0001x over previous
.LBB0_526:
	v_readlane_b32 s8, v252, 9
	v_readlane_b32 s9, v252, 10
	v_readlane_b32 s10, v253, 53
	s_waitcnt lgkmcnt(0)
	s_nop 4
	global_load_dword v0, v157, s[8:9] sc1
	global_load_dword v1, v157, s[8:9] offset:256 sc1
	global_load_dword v2, v157, s[8:9] offset:512 sc1
	global_load_dword v3, v157, s[8:9] offset:768 sc1
	global_load_dword v4, v157, s[8:9] offset:1024 sc1
	global_load_dword v5, v157, s[8:9] offset:1280 sc1
	global_load_dword v6, v157, s[8:9] offset:1536 sc1
	global_load_dword v7, v157, s[8:9] offset:1792 sc1
	global_load_dword v8, v157, s[8:9] offset:2048 sc1
	global_load_dword v9, v157, s[8:9] offset:2304 sc1
	global_load_dword v10, v157, s[8:9] offset:2560 sc1
	global_load_dword v11, v157, s[8:9] offset:2816 sc1
	global_load_dword v12, v157, s[8:9] offset:3072 sc1
	global_load_dword v13, v157, s[8:9] offset:3328 sc1
	global_load_dword v14, v157, s[8:9] offset:3584 sc1
	global_load_dword v15, v157, s[8:9] offset:3840 sc1
	s_mov_b64 s[8:9], -1
	s_waitcnt vmcnt(0)
	v_add_u32_e32 v16, v1, v0
	v_add_u32_e32 v16, v16, v2
	v_add_u32_e32 v16, v16, v3
	v_add_u32_e32 v16, v16, v4
	v_add_u32_e32 v16, v16, v5
	v_add_u32_e32 v16, v16, v6
	v_add_u32_e32 v16, v16, v7
	v_add_u32_e32 v16, v16, v8
	v_add_u32_e32 v16, v16, v9
	v_add_u32_e32 v16, v16, v10
	v_add_u32_e32 v16, v16, v11
	v_add_u32_e32 v16, v16, v12
	v_add_u32_e32 v16, v16, v13
	v_add_u32_e32 v16, v16, v14
	v_add_u32_e32 v16, v16, v15
	v_cmp_eq_u32_e32 vcc, s10, v16
	s_mov_b64 s[10:11], -1
	s_cbranch_vccnz .LBB0_525
	s_and_b32 s8, s14, 0xff
	s_cmp_eq_u32 s8, 0
	s_mov_b64 s[8:9], -1
	s_mov_b64 s[12:13], -1
	s_sleep 1
	s_cbranch_scc0 .LBB0_530
	v_readlane_b32 s8, v252, 7
	v_readlane_b32 s9, v252, 8
	s_nop 4
	global_load_dword v16, v157, s[8:9] sc1
	s_waitcnt vmcnt(0)
	v_cmp_eq_u32_e32 vcc, 0, v16
	s_cbranch_vccnz .LBB0_532
	s_mov_b64 s[12:13], 0
	s_mov_b64 s[8:9], -1

.LBB0_557:
	s_or_b64 exec, exec, s[10:11]
	s_waitcnt vmcnt(0)
	v_readfirstlane_b32 s8, v2
	v_cvt_f32_u32_e32 v2, v0
	v_sub_u32_e32 v3, 0, v0
	v_add_u32_e32 v1, s8, v1
	v_readlane_b32 s8, v253, 15
	v_rcp_iflag_f32_e32 v2, v2
	v_readlane_b32 s9, v253, 16
	s_mov_b64 s[10:11], -1
	v_mul_f32_e32 v2, 0x4f7ffffe, v2
	v_cvt_u32_f32_e32 v2, v2
	v_mul_lo_u32 v3, v3, v2
	v_mul_hi_u32 v3, v2, v3
	v_add_u32_e32 v2, v2, v3
	v_mul_hi_u32 v2, v1, v2
	v_mul_lo_u32 v3, v2, v0
	v_sub_u32_e32 v3, v1, v3
	v_cmp_ge_u32_e32 vcc, v3, v0
	v_add_u32_e32 v4, 1, v2
	v_add_u32_e32 v1, 1, v1
	v_cndmask_b32_e32 v2, v2, v4, vcc
	v_sub_u32_e32 v4, v3, v0
	v_cndmask_b32_e32 v3, v3, v4, vcc
	v_cmp_ge_u32_e32 vcc, v3, v0
	v_add_u32_e32 v3, 1, v2
	s_nop 0
	v_cndmask_b32_e32 v2, v2, v3, vcc
	v_mul_lo_u32 v3, v0, v2
	v_add_u32_e32 v0, v3, v0
	v_mov_b32_e32 v5, v0
	v_cmp_ne_u32_e32 vcc, v1, v0
	v_mov_b64_e32 v[0:1], s[8:9]
	s_and_saveexec_b64 s[8:9], vcc
	s_cbranch_execz .LBB0_569
	v_readlane_b32 s10, v253, 13
	v_readlane_b32 s11, v253, 14
	s_mov_b64 s[12:13], 0
	s_nop 3
	global_load_dword v0, v157, s[10:11] sc1
	s_waitcnt vmcnt(0)
	v_cmp_lt_u32_e32 vcc, v0, v5
	s_and_saveexec_b64 s[10:11], vcc
	s_cbranch_execz .LBB0_568
	s_mov_b32 s22, 1
	s_branch .LBB0_561

.LBB0_565:
	v_readlane_b32 s16, v253, 13
	v_readlane_b32 s17, v253, 14
	s_add_i32 s22, s22, 1
	s_mov_b64 s[18:19], -1
	s_nop 2
	global_load_dword v0, v157, s[16:17] sc1
	s_waitcnt vmcnt(0)
	v_cmp_ge_u32_e32 vcc, v0, v5
	s_orn2_b64 s[16:17], vcc, exec
	s_branch .LBB0_560
